# job0 PV: transposed V fragment reads one k-step ahead (8 in flight), MFMA pairs straight-line
# speedup vs baseline: 1.0031x; 1.0031x over previous
.LBB0_1070:
	s_nop 3
	v_add_u32_e32 v90, v197, v200
	ds_read_b64_tr_b16 v[220:221], v90 offset:9216
	ds_read_b64_tr_b16 v[222:223], v90 offset:10368
	ds_read_b64_tr_b16 v[224:225], v90 offset:9280
	ds_read_b64_tr_b16 v[226:227], v90 offset:10432
	ds_read_b64_tr_b16 v[228:229], v90 offset:11520
	ds_read_b64_tr_b16 v[230:231], v90 offset:12672
	ds_read_b64_tr_b16 v[232:233], v90 offset:11584
	ds_read_b64_tr_b16 v[234:235], v90 offset:12736
	s_and_b64 vcc, exec, s[12:13]
	s_cbranch_vccnz .Lj0p1_a0
	s_waitcnt lgkmcnt(6)
	v_mfma_f32_32x32x16_bf16 v[50:65], v[220:223], v[110:113], v[50:65]
	s_waitcnt lgkmcnt(4)
	v_mfma_f32_32x32x16_bf16 v[34:49], v[224:227], v[110:113], v[34:49]
.Lj0p1_a0:
	s_and_b64 vcc, exec, s[10:11]
	s_cbranch_vccnz .Lj0p1_b0
	s_waitcnt lgkmcnt(6)
	v_mfma_f32_32x32x16_bf16 v[2:17], v[220:223], v[78:81], v[2:17]
	s_waitcnt lgkmcnt(4)
	v_mfma_f32_32x32x16_bf16 v[18:33], v[224:227], v[78:81], v[18:33]
.Lj0p1_b0:
	ds_read_b64_tr_b16 v[236:237], v90 offset:13824
	ds_read_b64_tr_b16 v[238:239], v90 offset:14976
	ds_read_b64_tr_b16 v[240:241], v90 offset:13888
	ds_read_b64_tr_b16 v[242:243], v90 offset:15040
	s_and_b64 vcc, exec, s[12:13]
	s_cbranch_vccnz .Lj0p1_a1
	s_waitcnt lgkmcnt(6)
	v_mfma_f32_32x32x16_bf16 v[50:65], v[228:231], v[106:109], v[50:65]
	s_waitcnt lgkmcnt(4)
	v_mfma_f32_32x32x16_bf16 v[34:49], v[232:235], v[106:109], v[34:49]
.Lj0p1_a1:
	s_and_b64 vcc, exec, s[10:11]
	s_cbranch_vccnz .Lj0p1_b1
	s_waitcnt lgkmcnt(6)
	v_mfma_f32_32x32x16_bf16 v[2:17], v[228:231], v[74:77], v[2:17]
	s_waitcnt lgkmcnt(4)
	v_mfma_f32_32x32x16_bf16 v[18:33], v[232:235], v[74:77], v[18:33]
.Lj0p1_b1:
	ds_read_b64_tr_b16 v[246:247], v90 offset:16128
	ds_read_b64_tr_b16 v[248:249], v90 offset:17280
	ds_read_b64_tr_b16 v[250:251], v90 offset:16192
	ds_read_b64_tr_b16 v[252:253], v90 offset:17344
	s_and_b64 vcc, exec, s[12:13]
	s_cbranch_vccnz .Lj0p1_a2
	s_waitcnt lgkmcnt(6)
	v_mfma_f32_32x32x16_bf16 v[50:65], v[236:239], v[102:105], v[50:65]
	s_waitcnt lgkmcnt(4)
	v_mfma_f32_32x32x16_bf16 v[34:49], v[240:243], v[102:105], v[34:49]

.LBB0_1127:
	s_nop 3
	v_add_u32_e32 v90, v197, v200
	ds_read_b64_tr_b16 v[220:221], v90 offset:41984
	ds_read_b64_tr_b16 v[222:223], v90 offset:43136
	ds_read_b64_tr_b16 v[224:225], v90 offset:42048
	ds_read_b64_tr_b16 v[226:227], v90 offset:43200
	ds_read_b64_tr_b16 v[228:229], v90 offset:44288
	ds_read_b64_tr_b16 v[230:231], v90 offset:45440
	ds_read_b64_tr_b16 v[232:233], v90 offset:44352
	ds_read_b64_tr_b16 v[234:235], v90 offset:45504
	s_and_b64 vcc, exec, s[12:13]
	s_cbranch_vccnz .Lj0p2_a0
	s_waitcnt lgkmcnt(6)
	v_mfma_f32_32x32x16_bf16 v[50:65], v[220:223], v[110:113], v[50:65]
	s_waitcnt lgkmcnt(4)
	v_mfma_f32_32x32x16_bf16 v[34:49], v[224:227], v[110:113], v[34:49]

.Lj0p2_b0:
	ds_read_b64_tr_b16 v[236:237], v90 offset:46592
	ds_read_b64_tr_b16 v[238:239], v90 offset:47744
	ds_read_b64_tr_b16 v[240:241], v90 offset:46656
	ds_read_b64_tr_b16 v[242:243], v90 offset:47808
	s_and_b64 vcc, exec, s[12:13]
	s_cbranch_vccnz .Lj0p2_a1
	s_waitcnt lgkmcnt(6)
	v_mfma_f32_32x32x16_bf16 v[50:65], v[228:231], v[106:109], v[50:65]
	s_waitcnt lgkmcnt(4)
	v_mfma_f32_32x32x16_bf16 v[34:49], v[232:235], v[106:109], v[34:49]

.Lj0p2_b1:
	ds_read_b64_tr_b16 v[246:247], v90 offset:48896
	ds_read_b64_tr_b16 v[248:249], v90 offset:50048
	ds_read_b64_tr_b16 v[250:251], v90 offset:48960
	ds_read_b64_tr_b16 v[252:253], v90 offset:50112
	s_and_b64 vcc, exec, s[12:13]
	s_cbranch_vccnz .Lj0p2_a2
	s_waitcnt lgkmcnt(6)
	v_mfma_f32_32x32x16_bf16 v[50:65], v[236:239], v[102:105], v[50:65]
	s_waitcnt lgkmcnt(4)
	v_mfma_f32_32x32x16_bf16 v[34:49], v[240:243], v[102:105], v[34:49]
